# LRU phase: gates/scan/carry kept in MFMA accumulator layout registers (x via 2 select MFMAs), only h through LDS
# speedup vs baseline: 1.0253x; 1.0253x over previous
.LBB0_359:
	s_or_b64 exec, exec, s[72:73]
	s_bfe_u32 s25, s11, 0x20003
	s_lshl_b32 s3, s25, 5
	s_or_b32 s1, s0, s3
	v_or_b32_e32 v2, s1, v116
	v_lshlrev_b32_e32 v8, 2, v2
	v_add_u32_e32 v0, s1, v79
	global_load_dword v10, v8, s[60:61]
	v_ashrrev_i32_e32 v1, 31, v0
	v_lshlrev_b64 v[0:1], 8, v[0:1]
	v_lshl_or_b32 v0, v78, 1, v0
	v_lshl_add_u64 v[2:3], s[42:43], 0, v[0:1]
	v_lshl_add_u64 v[4:5], s[44:45], 0, v[0:1]
	global_load_dwordx4 v[0:3], v[2:3], off
	s_nop 0
	global_load_dwordx4 v[4:7], v[4:5], off
	s_lshl_b32 s1, s11, 7
	s_and_b32 s18, s1, 0xfffff000
	s_ashr_i32 s19, s18, 31
	s_lshl_b64 s[22:23], s[18:19], 11
	s_add_u32 s1, s57, s22
	s_addc_u32 s16, s63, s23
	s_lshl_b32 s0, s0, 1
	s_add_u32 s20, s1, s0
	s_addc_u32 s21, s16, 0
	global_load_dword v12, v8, s[54:55]
	global_load_dword v13, v8, s[58:59]
	v_lshl_add_u64 v[8:9], s[20:21], 0, v[82:83]
	v_lshl_add_u64 v[20:21], s[20:21], 0, v[84:85]
	v_lshl_add_u64 v[24:25], s[20:21], 0, v[86:87]
	v_lshl_add_u64 v[28:29], s[20:21], 0, v[88:89]
	v_lshl_add_u64 v[32:33], s[20:21], 0, v[90:91]
	v_lshl_add_u64 v[34:35], s[20:21], 0, v[92:93]
	v_lshl_add_u64 v[36:37], s[20:21], 0, v[94:95]
	v_lshl_add_u64 v[38:39], s[20:21], 0, v[96:97]
	v_lshl_add_u64 v[40:41], s[20:21], 0, v[98:99]
	v_lshl_add_u64 v[42:43], s[20:21], 0, v[100:101]
	global_load_dwordx4 v[16:19], v[8:9], off
	s_nop 0
	global_load_dwordx4 v[20:23], v[20:21], off
	s_nop 0
	global_load_dwordx4 v[24:27], v[24:25], off
	s_nop 0
	global_load_dwordx4 v[28:31], v[28:29], off
	s_nop 0
	global_load_dwordx4 v[48:51], v[32:33], off
	global_load_dwordx4 v[52:55], v[34:35], off
	global_load_dwordx4 v[56:59], v[36:37], off
	global_load_dwordx4 v[60:63], v[38:39], off
	global_load_dwordx4 v[64:67], v[40:41], off
	global_load_dwordx4 v[68:71], v[42:43], off
	v_lshl_add_u64 v[44:45], s[20:21], 0, v[102:103]
	v_add_u32_e32 v14, 0x22a00, v124
	v_add_u32_e32 v15, 0x24a00, v124
	s_add_u32 s1, s65, s22
	s_mov_b32 s24, 0
	s_waitcnt vmcnt(14)
	v_mul_f32_e32 v8, 0xbfb8aa3b, v10
	v_exp_f32_e32 v36, v8
	global_load_dwordx4 v[8:11], v[44:45], off
	s_waitcnt vmcnt(14)
	ds_write_b128 v14, v[0:3]
	s_waitcnt vmcnt(13)
	ds_write_b128 v15, v[4:7]
	v_add_f32_e32 v2, 1.0, v36
	v_add_f32_e32 v3, -1.0, v2
	v_frexp_mant_f32_e32 v4, v2
	v_cvt_f64_f32_e32 v[0:1], v2
	v_sub_f32_e32 v5, v3, v2
	v_frexp_exp_i32_f64_e32 v0, v[0:1]
	v_cmp_gt_f32_e64 s[16:17], s94, v4
	v_sub_f32_e32 v3, v36, v3
	v_add_f32_e32 v1, 1.0, v5
	v_subbrev_co_u32_e64 v0, s[16:17], 0, v0, s[16:17]
	v_add_f32_e32 v1, v3, v1
	v_sub_u32_e32 v3, 0, v0
	v_ldexp_f32 v2, v2, v3
	v_add_f32_e32 v4, -1.0, v2
	v_add_f32_e32 v5, 1.0, v2
	v_ldexp_f32 v1, v1, v3
	v_add_f32_e32 v3, 1.0, v4
	v_add_f32_e32 v6, -1.0, v5
	v_sub_f32_e32 v3, v2, v3
	v_sub_f32_e32 v2, v2, v6
	v_add_f32_e32 v6, v1, v3
	v_add_f32_e32 v1, v1, v2
	v_add_f32_e32 v14, v5, v1
	v_rcp_f32_e32 v15, v14
	v_add_f32_e32 v3, v4, v6
	v_sub_f32_e32 v4, v3, v4
	v_sub_f32_e32 v2, v14, v5
	v_mul_f32_e32 v33, v3, v15
	v_sub_f32_e32 v32, v6, v4
	v_mul_f32_e32 v4, v14, v33
	v_sub_f32_e32 v1, v1, v2
	v_fma_f32 v6, v33, v14, -v4
	v_fmac_f32_e32 v6, v33, v1
	v_add_f32_e32 v2, v4, v6
	v_sub_f32_e32 v5, v3, v2
	v_mov_b32_e32 v7, v2
	v_pk_add_f32 v[2:3], v[2:3], v[4:5] neg_lo:[0,1] neg_hi:[0,1]
	v_cvt_f32_i32_e32 v0, v0
	v_pk_add_f32 v[2:3], v[2:3], v[6:7] neg_lo:[0,1] neg_hi:[0,1]
	v_cmp_neq_f32_e64 s[16:17], s96, v36
	v_add_f32_e32 v3, v32, v3
	v_add_f32_e32 v2, v2, v3
	v_add_f32_e32 v3, v5, v2
	v_mul_f32_e32 v7, v15, v3
	v_mul_f32_e32 v4, v14, v7
	v_sub_f32_e32 v5, v5, v3
	v_add_f32_e32 v34, v33, v7
	v_fma_f32 v6, v7, v14, -v4
	v_add_f32_e32 v32, v2, v5
	v_sub_f32_e32 v2, v34, v33
	v_fmac_f32_e32 v6, v7, v1
	v_sub_f32_e32 v1, v7, v2
	v_add_f32_e32 v2, v4, v6
	v_sub_f32_e32 v5, v3, v2
	v_mov_b32_e32 v7, v2
	v_pk_add_f32 v[2:3], v[2:3], v[4:5] neg_lo:[0,1] neg_hi:[0,1]
	s_waitcnt vmcnt(12)
	v_mul_f32_e32 v108, 0xbfb8aa3b, v12
	v_pk_add_f32 v[2:3], v[2:3], v[6:7] neg_lo:[0,1] neg_hi:[0,1]
	s_waitcnt vmcnt(11)
	v_mul_f32_e32 v110, 0xbfb8aa3b, v13
	v_add_f32_e32 v3, v32, v3
	v_add_f32_e32 v2, v2, v3
	v_add_f32_e32 v2, v5, v2
	v_mul_f32_e32 v2, v15, v2
	v_add_f32_e32 v1, v1, v2
	v_add_f32_e32 v2, v34, v1
	v_mul_f32_e32 v4, v2, v2
	v_sub_f32_e32 v5, v2, v34
	v_fmamk_f32 v6, v4, 0x3e9b6dac, v125
	v_sub_f32_e32 v5, v1, v5
	v_mul_f32_e32 v1, v2, v4
	v_fmaak_f32 v105, v4, v6, 0x3f2aaada
	v_ldexp_f32 v7, v5, 1
	v_pk_mul_f32 v[4:5], v[0:1], v[104:105]
	v_ldexp_f32 v3, v2, 1
	v_fma_f32 v2, v0, s95, -v4
	v_fmac_f32_e32 v2, 0xb102e308, v0
	v_pk_add_f32 v[0:1], v[4:5], v[2:3]
	v_mov_b32_e32 v6, v4
	v_sub_f32_e32 v32, v1, v3
	v_pk_add_f32 v[14:15], v[0:1], v[4:5] neg_lo:[0,1] neg_hi:[0,1]
	v_sub_f32_e32 v4, v5, v32
	v_add_f32_e32 v7, v7, v4
	v_pk_add_f32 v[4:5], v[0:1], v[6:7]
	v_mov_b32_e32 v3, v0
	v_mov_b32_e32 v15, v5
	v_pk_add_f32 v[34:35], v[2:3], v[14:15] neg_lo:[0,1] neg_hi:[0,1]
	v_pk_add_f32 v[2:3], v[2:3], v[14:15]
	v_mov_b32_e32 v32, v5
	v_pk_add_f32 v[14:15], v[2:3], v[0:1] op_sel:[1,0] op_sel_hi:[0,1] neg_lo:[0,1] neg_hi:[0,1]
	v_mov_b32_e32 v33, v3
	v_pk_add_f32 v[4:5], v[4:5], v[14:15] op_sel_hi:[1,0] neg_lo:[0,1] neg_hi:[0,1]
	v_pk_mov_b32 v[14:15], v[0:1], v[14:15] op_sel:[1,0]
	v_mov_b32_e32 v6, v7
	v_pk_add_f32 v[14:15], v[32:33], v[14:15] neg_lo:[0,1] neg_hi:[0,1]
	v_mov_b32_e32 v7, v0
	v_pk_add_f32 v[0:1], v[6:7], v[14:15] neg_lo:[0,1] neg_hi:[0,1]
	v_mov_b32_e32 v4, v34
	v_pk_add_f32 v[4:5], v[4:5], v[0:1]
	v_mov_b32_e32 v35, v3
	v_pk_add_f32 v[6:7], v[4:5], v[4:5] op_sel:[0,1] op_sel_hi:[1,0]
	s_waitcnt vmcnt(10)
	v_cndmask_b32_e64 v33, v17, 0, s[4:5]
	v_pk_add_f32 v[2:3], v[2:3], v[6:7] op_sel:[1,0] op_sel_hi:[0,1]
	v_mov_b32_e32 v5, v2
	v_pk_add_f32 v[14:15], v[4:5], v[34:35] neg_lo:[0,1] neg_hi:[0,1]
	v_mov_b32_e32 v1, v6
	v_sub_f32_e32 v3, v4, v14
	v_pk_add_f32 v[0:1], v[0:1], v[14:15] neg_lo:[0,1] neg_hi:[0,1]
	v_sub_f32_e32 v3, v34, v3
	v_add_f32_e32 v0, v0, v3
	v_add_f32_e32 v0, v0, v1
	v_add_f32_e32 v0, v2, v0
	v_cndmask_b32_e64 v0, v127, v0, s[16:17]
	v_cmp_ngt_f32_e64 s[16:17], -1.0, v36
	v_cndmask_b32_e64 v35, v19, 0, s[4:5]
	v_cndmask_b32_e64 v34, v18, 0, s[4:5]
	v_cndmask_b32_e64 v0, v128, v0, s[16:17]
	v_cmp_neq_f32_e64 s[16:17], -1.0, v36
	v_cndmask_b32_e64 v32, v16, 0, s[4:5]
	s_waitcnt vmcnt(9)
	v_cndmask_b32_e64 v39, v23, 0, s[4:5]
	v_cndmask_b32_e64 v0, v129, v0, s[16:17]
	v_cmp_lt_f32_e64 s[16:17], |v36|, s97
	v_cndmask_b32_e64 v38, v22, 0, s[4:5]
	v_cndmask_b32_e64 v37, v21, 0, s[4:5]
	v_cndmask_b32_e64 v0, v0, v36, s[16:17]
	s_addc_u32 s16, s67, s23
	s_add_u32 s0, s1, s0
	s_addc_u32 s1, s16, 0
	s_lshl_b32 s16, s25, 6
	s_add_u32 s22, s0, s16
	s_addc_u32 s23, s1, 0
	s_lshl_b64 s[0:1], s[18:19], 2
	s_add_u32 s0, s30, s0
	s_addc_u32 s1, s31, s1
	s_lshl_b32 s16, s52, 19
	s_lshl_b32 s17, s25, 17
	v_mul_f32_e32 v0, 0x41000000, v0
	s_or_b32 s16, s17, s16
	v_mul_f32_e32 v106, 0xbfb8aa3b, v0
	v_mul_f32_e32 v112, -2.0, v0
	s_add_u32 s25, s0, s16
	v_cndmask_b32_e64 v36, v20, 0, s[4:5]
	s_waitcnt vmcnt(8)
	v_cndmask_b32_e64 v43, v27, 0, s[4:5]
	v_cndmask_b32_e64 v42, v26, 0, s[4:5]
	v_cndmask_b32_e64 v41, v25, 0, s[4:5]
	v_cndmask_b32_e64 v40, v24, 0, s[4:5]
	s_waitcnt vmcnt(7)
	v_cndmask_b32_e64 v47, v31, 0, s[6:7]
	v_cndmask_b32_e64 v46, v30, 0, s[6:7]
	v_cndmask_b32_e64 v45, v29, 0, s[6:7]
	v_cndmask_b32_e64 v44, v28, 0, s[6:7]
	s_waitcnt vmcnt(6)
	v_cndmask_b32_e64 v51, v51, 0, s[6:7]
	v_cndmask_b32_e64 v50, v50, 0, s[6:7]
	v_cndmask_b32_e64 v49, v49, 0, s[6:7]
	v_cndmask_b32_e64 v48, v48, 0, s[6:7]
	s_waitcnt vmcnt(5)
	v_cndmask_b32_e64 v55, v55, 0, s[6:7]
	v_cndmask_b32_e64 v54, v54, 0, s[6:7]
	v_cndmask_b32_e64 v53, v53, 0, s[6:7]
	v_cndmask_b32_e64 v52, v52, 0, s[6:7]
	s_waitcnt vmcnt(4)
	v_cndmask_b32_e64 v59, v59, 0, s[6:7]
	v_cndmask_b32_e64 v58, v58, 0, s[6:7]
	v_cndmask_b32_e64 v57, v57, 0, s[6:7]
	v_cndmask_b32_e64 v56, v56, 0, s[6:7]
	s_waitcnt vmcnt(3)
	v_cndmask_b32_e64 v63, v63, 0, s[6:7]
	v_cndmask_b32_e64 v62, v62, 0, s[6:7]
	v_cndmask_b32_e64 v61, v61, 0, s[6:7]
	v_cndmask_b32_e64 v60, v60, 0, s[6:7]
	s_waitcnt vmcnt(2)
	v_cndmask_b32_e64 v67, v67, 0, s[6:7]
	v_cndmask_b32_e64 v66, v66, 0, s[6:7]
	v_cndmask_b32_e64 v65, v65, 0, s[6:7]
	v_cndmask_b32_e64 v64, v64, 0, s[6:7]
	s_waitcnt vmcnt(1)
	v_cndmask_b32_e64 v71, v71, 0, s[6:7]
	v_cndmask_b32_e64 v70, v70, 0, s[6:7]
	v_cndmask_b32_e64 v69, v69, 0, s[6:7]
	v_cndmask_b32_e64 v68, v68, 0, s[6:7]
	s_waitcnt vmcnt(0)
	v_cndmask_b32_e64 v75, v11, 0, s[6:7]
	v_cndmask_b32_e64 v74, v10, 0, s[6:7]
	v_cndmask_b32_e64 v73, v9, 0, s[6:7]
	v_cndmask_b32_e64 v72, v8, 0, s[6:7]
	v_mov_b32_e32 v109, v108
	v_mov_b32_e32 v111, v110
	v_mov_b32_e32 v107, v106
	v_mov_b32_e32 v113, v112
	s_addc_u32 s26, s1, 0
	v_mov_b32_e32 v105, 0
	s_waitcnt lgkmcnt(0)
	v_bfe_u32 v234, v76, 5, 1
	v_bfe_u32 v235, v116, 3, 1
	v_and_b32_e32 v236, 1, v116
	v_lshlrev_b32_e32 v236, 4, v236
	v_mov_b32_e32 v237, 0x3c00
	v_cmp_eq_u32_e32 vcc, v234, v235
	v_lshlrev_b32_e32 v237, v236, v237
	s_nop 1
	v_cndmask_b32_e32 v237, 0, v237, vcc
	v_bfe_u32 v238, v116, 1, 2
	v_cmp_gt_u32_e64 s[16:17], 16, v116
	v_cmp_eq_u32_e32 vcc, 0, v238
	s_nop 1
	v_cndmask_b32_e32 v239, 0, v237, vcc
	s_nop 0
	v_cndmask_b32_e64 v168, 0, v239, s[16:17]
	v_cndmask_b32_e64 v172, v239, 0, s[16:17]
	v_cmp_eq_u32_e32 vcc, 1, v238
	s_nop 1
	v_cndmask_b32_e32 v239, 0, v237, vcc
	s_nop 0
	v_cndmask_b32_e64 v169, 0, v239, s[16:17]
	v_cndmask_b32_e64 v173, v239, 0, s[16:17]
	v_cmp_eq_u32_e32 vcc, 2, v238
	s_nop 1
	v_cndmask_b32_e32 v239, 0, v237, vcc
	s_nop 0
	v_cndmask_b32_e64 v170, 0, v239, s[16:17]
	v_cndmask_b32_e64 v174, v239, 0, s[16:17]
	v_cmp_eq_u32_e32 vcc, 3, v238
	s_nop 1
	v_cndmask_b32_e32 v239, 0, v237, vcc
	s_nop 0
	v_cndmask_b32_e64 v171, 0, v239, s[16:17]
	v_cndmask_b32_e64 v175, v239, 0, s[16:17]
	s_barrier
	s_branch .LBB0_361
.LBB0_360:
	s_or_b64 exec, exec, s[18:19]
	s_add_i32 s24, s24, 1
	s_cmp_eq_u32 s24, 16
	s_cbranch_scc1 .LBB0_339

.LBB0_363:
	v_bfe_u32 v80, v115, 5, 1
	v_and_b32_e32 v133, 31, v115
	v_lshlrev_b32_e32 v132, 8, v133
	v_lshlrev_b32_e32 v146, 4, v80
	v_lshlrev_b32_e32 v0, 4, v115
	v_and_b32_e32 v147, 0x70, v0
	v_add_u32_e32 v148, s90, v132
	v_bitop3_b32 v0, v146, v0, s69 bitop3:0x78
	s_waitcnt lgkmcnt(0)
	v_add_u32_e32 v0, v148, v0
	ds_read_b128 v[16:19], v0
	v_bitop3_b32 v24, v146, v147, 32 bitop3:0x36
	v_bitop3_b32 v20, v146, v132, v147 bitop3:0xde
	s_add_i32 s0, 0, 0x22a00
	s_add_i32 s1, 0, 0x24a00
	v_add_u32_e32 v24, v148, v24
	ds_read_b128 v[134:137], v24
	v_add_u32_e32 v0, s0, v20
	v_add_u32_e32 v20, s1, v20
	ds_read_b128 v[0:3], v0
	ds_read_b128 v[20:23], v20
	s_waitcnt lgkmcnt(1)
	v_mfma_f32_32x32x16_f16 v[0:15], v[16:19], v[0:3], 0
	v_or_b32_e32 v138, 32, v146
	v_bitop3_b32 v142, v138, v132, v147 bitop3:0xde
	v_add_u32_e32 v138, s0, v142
	v_add_u32_e32 v142, s1, v142
	ds_read_b128 v[138:141], v138
	ds_read_b128 v[142:145], v142
	v_or_b32_e32 v149, 0x60, v146
	s_waitcnt lgkmcnt(2)
	v_mfma_f32_32x32x16_f16 v[16:31], v[16:19], v[20:23], 0
	s_movk_i32 s16, 0x80
	v_lshlrev_b32_e32 v80, 7, v80
	v_or3_b32 v80, v80, s91, v133
	v_lshlrev_b32_e32 v80, 2, v80
	s_waitcnt lgkmcnt(1)
	v_mfma_f32_32x32x16_f16 v[0:15], v[134:137], v[138:141], v[0:15]
	v_or_b32_e32 v138, 64, v146
	s_waitcnt lgkmcnt(0)
	v_mfma_f32_32x32x16_f16 v[16:31], v[134:137], v[142:145], v[16:31]
	v_bitop3_b32 v134, v146, v147, 64 bitop3:0x36
	v_add_u32_e32 v134, v148, v134
	ds_read_b128 v[134:137], v134
	v_bitop3_b32 v142, v138, v132, v147 bitop3:0xde
	v_add_u32_e32 v138, s0, v142
	ds_read_b128 v[138:141], v138
	s_waitcnt lgkmcnt(0)
	v_mfma_f32_32x32x16_f16 v[0:15], v[134:137], v[138:141], v[0:15]
	v_add_u32_e32 v138, s1, v142
	ds_read_b128 v[138:141], v138
	v_bitop3_b32 v142, v146, v147, s83 bitop3:0x36
	v_add_u32_e32 v142, v148, v142
	ds_read_b128 v[142:145], v142
	s_waitcnt lgkmcnt(1)
	v_mfma_f32_32x32x16_f16 v[16:31], v[134:137], v[138:141], v[16:31]
	v_bitop3_b32 v138, v149, v132, v147 bitop3:0xde
	v_add_u32_e32 v134, s0, v138
	ds_read_b128 v[134:137], v134
	v_add_u32_e32 v138, s1, v138
	ds_read_b128 v[138:141], v138
	v_or_b32_e32 v149, 0x80, v146
	s_waitcnt lgkmcnt(1)
	v_mfma_f32_32x32x16_f16 v[0:15], v[142:145], v[134:137], v[0:15]
	v_bitop3_b32 v134, v146, v147, s16 bitop3:0x36
	v_add_u32_e32 v134, v148, v134
	ds_read_b128 v[134:137], v134
	s_waitcnt lgkmcnt(1)
	v_mfma_f32_32x32x16_f16 v[16:31], v[142:145], v[138:141], v[16:31]
	v_bitop3_b32 v142, v149, v132, v147 bitop3:0xde
	v_add_u32_e32 v138, s0, v142
	ds_read_b128 v[138:141], v138
	v_or_b32_e32 v149, 0xa0, v146
	s_waitcnt lgkmcnt(0)
	v_mfma_f32_32x32x16_f16 v[0:15], v[134:137], v[138:141], v[0:15]
	v_add_u32_e32 v138, s1, v142
	ds_read_b128 v[138:141], v138
	v_bitop3_b32 v142, v146, v147, s80 bitop3:0x36
	v_add_u32_e32 v142, v148, v142
	ds_read_b128 v[142:145], v142
	s_waitcnt lgkmcnt(1)
	v_mfma_f32_32x32x16_f16 v[16:31], v[134:137], v[138:141], v[16:31]
	v_bitop3_b32 v138, v149, v132, v147 bitop3:0xde
	v_add_u32_e32 v134, s0, v138
	ds_read_b128 v[134:137], v134
	v_add_u32_e32 v138, s1, v138
	ds_read_b128 v[138:141], v138
	v_or_b32_e32 v149, 0xc0, v146
	s_waitcnt lgkmcnt(1)
	v_mfma_f32_32x32x16_f16 v[0:15], v[142:145], v[134:137], v[0:15]
	v_bitop3_b32 v134, v146, v147, s81 bitop3:0x36
	v_add_u32_e32 v134, v148, v134
	ds_read_b128 v[134:137], v134
	s_waitcnt lgkmcnt(1)
	v_mfma_f32_32x32x16_f16 v[16:31], v[142:145], v[138:141], v[16:31]
	v_bitop3_b32 v142, v149, v132, v147 bitop3:0xde
	v_add_u32_e32 v138, s0, v142
	ds_read_b128 v[138:141], v138
	v_or_b32_e32 v149, 0xe0, v146
	v_bitop3_b32 v132, v149, v132, v147 bitop3:0xde
	s_waitcnt lgkmcnt(0)
	v_mfma_f32_32x32x16_f16 v[0:15], v[134:137], v[138:141], v[0:15]
	v_add_u32_e32 v138, s1, v142
	ds_read_b128 v[138:141], v138
	v_bitop3_b32 v142, v146, v147, s38 bitop3:0x36
	v_add_u32_e32 v142, v148, v142
	ds_read_b128 v[142:145], v142
	s_waitcnt lgkmcnt(1)
	v_mfma_f32_32x32x16_f16 v[16:31], v[134:137], v[138:141], v[16:31]
	v_add_u32_e32 v134, s0, v132
	ds_read_b128 v[134:137], v134
	v_add_u32_e32 v132, s1, v132
	ds_read_b128 v[138:141], v132
	v_and_b32_e32 v132, 1, v115
	s_lshl_b32 s0, s24, 19
	s_mov_b32 s1, -2
	s_waitcnt lgkmcnt(1)
	v_mfma_f32_32x32x16_f16 v[0:15], v[142:145], v[134:137], v[0:15]
	v_add_u32_e32 v134, s39, v80
	s_waitcnt lgkmcnt(0)
	v_mfma_f32_32x32x16_f16 v[16:31], v[142:145], v[138:141], v[16:31]
	s_lshl_b32 s18, s3, 1
	s_add_i32 s19, s18, 32
	v_bitop3_b32 v134, v146, v147, s18 bitop3:0x36
	v_add_u32_e32 v134, v148, v134
	ds_read_b128 v[134:137], v134
	v_bitop3_b32 v138, v146, v147, s19 bitop3:0x36
	v_add_u32_e32 v138, v148, v138
	ds_read_b128 v[138:141], v138
	v_add_u32_e32 v250, s33, v80
	s_waitcnt lgkmcnt(1)
	v_mfma_f32_32x32x16_f16 v[152:167], v[134:137], v[168:171], 0
	s_waitcnt lgkmcnt(0)
	v_mfma_f32_32x32x16_f16 v[152:167], v[138:141], v[172:175], v[152:167]
	v_lshl_or_b32 v251, v132, 5, s0
	v_lshl_add_u32 v80, v114, 11, v251
	global_load_dwordx4 v[240:243], v80, s[22:23] offset:16
	global_load_dwordx4 v[244:247], v80, s[22:23]
	v_lshl_add_u64 v[248:249], s[22:23], 0, v[80:81]
	s_nop 4
	v_pk_fma_f32 v[0:1], v[0:1], s[56:57], v[108:109] op_sel_hi:[1,0,1] neg_lo:[1,0,0] neg_hi:[1,0,0]
	v_pk_fma_f32 v[4:5], v[4:5], s[56:57], v[108:109] op_sel_hi:[1,0,1] neg_lo:[1,0,0] neg_hi:[1,0,0]
	v_pk_fma_f32 v[8:9], v[8:9], s[56:57], v[108:109] op_sel_hi:[1,0,1] neg_lo:[1,0,0] neg_hi:[1,0,0]
	v_pk_fma_f32 v[12:13], v[12:13], s[56:57], v[108:109] op_sel_hi:[1,0,1] neg_lo:[1,0,0] neg_hi:[1,0,0]
	v_pk_fma_f32 v[16:17], v[16:17], s[56:57], v[110:111] op_sel_hi:[1,0,1] neg_lo:[1,0,0] neg_hi:[1,0,0]
	v_pk_fma_f32 v[20:21], v[20:21], s[56:57], v[110:111] op_sel_hi:[1,0,1] neg_lo:[1,0,0] neg_hi:[1,0,0]
	v_pk_fma_f32 v[24:25], v[24:25], s[56:57], v[110:111] op_sel_hi:[1,0,1] neg_lo:[1,0,0] neg_hi:[1,0,0]
	v_pk_fma_f32 v[28:29], v[28:29], s[56:57], v[110:111] op_sel_hi:[1,0,1] neg_lo:[1,0,0] neg_hi:[1,0,0]
	v_pk_fma_f32 v[18:19], v[18:19], s[56:57], v[110:111] op_sel_hi:[1,0,1] neg_lo:[1,0,0] neg_hi:[1,0,0]
	v_pk_fma_f32 v[22:23], v[22:23], s[56:57], v[110:111] op_sel_hi:[1,0,1] neg_lo:[1,0,0] neg_hi:[1,0,0]
	v_pk_fma_f32 v[26:27], v[26:27], s[56:57], v[110:111] op_sel_hi:[1,0,1] neg_lo:[1,0,0] neg_hi:[1,0,0]
	v_pk_fma_f32 v[30:31], v[30:31], s[56:57], v[110:111] op_sel_hi:[1,0,1] neg_lo:[1,0,0] neg_hi:[1,0,0]
	v_min_f32_e32 v191, 0x42700000, v0
	v_min_f32_e32 v205, 0x42700000, v4
	v_min_f32_e32 v219, 0x42700000, v8
	v_min_f32_e32 v233, 0x42700000, v12
	v_min_f32_e32 v1, 0x42700000, v1
	v_min_f32_e32 v5, 0x42700000, v5
	v_min_f32_e32 v9, 0x42700000, v9
	v_min_f32_e32 v13, 0x42700000, v13
	v_min_f32_e32 v181, 0x42700000, v16
	v_min_f32_e32 v195, 0x42700000, v20
	v_min_f32_e32 v209, 0x42700000, v24
	v_min_f32_e32 v223, 0x42700000, v28
	v_min_f32_e32 v182, 0x42700000, v17
	v_min_f32_e32 v196, 0x42700000, v21
	v_min_f32_e32 v210, 0x42700000, v25
	v_min_f32_e32 v224, 0x42700000, v29
	v_min_f32_e32 v190, 0x42700000, v18
	v_min_f32_e32 v204, 0x42700000, v22
	v_min_f32_e32 v218, 0x42700000, v26
	v_min_f32_e32 v232, 0x42700000, v30
	v_min_f32_e32 v183, 0x42700000, v19
	v_min_f32_e32 v197, 0x42700000, v23
	v_min_f32_e32 v211, 0x42700000, v27
	v_min_f32_e32 v225, 0x42700000, v31
	v_exp_f32_e32 v16, v191
	v_exp_f32_e32 v20, v205
	v_exp_f32_e32 v24, v219
	v_exp_f32_e32 v28, v233
	v_exp_f32_e32 v17, v1
	v_exp_f32_e32 v21, v5
	v_exp_f32_e32 v25, v9
	v_exp_f32_e32 v29, v13
	v_exp_f32_e32 v18, v181
	v_exp_f32_e32 v22, v195
	v_exp_f32_e32 v26, v209
	v_exp_f32_e32 v30, v223
	v_exp_f32_e32 v19, v182
	v_exp_f32_e32 v23, v196
	v_exp_f32_e32 v27, v210
	v_exp_f32_e32 v31, v224
	v_pk_fma_f32 v[2:3], v[2:3], s[56:57], v[108:109] op_sel_hi:[1,0,1] neg_lo:[1,0,0] neg_hi:[1,0,0]
	v_pk_fma_f32 v[6:7], v[6:7], s[56:57], v[108:109] op_sel_hi:[1,0,1] neg_lo:[1,0,0] neg_hi:[1,0,0]
	v_pk_fma_f32 v[10:11], v[10:11], s[56:57], v[108:109] op_sel_hi:[1,0,1] neg_lo:[1,0,0] neg_hi:[1,0,0]
	v_pk_fma_f32 v[14:15], v[14:15], s[56:57], v[108:109] op_sel_hi:[1,0,1] neg_lo:[1,0,0] neg_hi:[1,0,0]
	v_exp_f32_e32 v180, v190
	v_exp_f32_e32 v194, v204
	v_exp_f32_e32 v208, v218
	v_exp_f32_e32 v222, v232
	v_min_f32_e32 v190, 0x42700000, v2
	v_min_f32_e32 v204, 0x42700000, v6
	v_min_f32_e32 v218, 0x42700000, v10
	v_min_f32_e32 v232, 0x42700000, v14
	v_min_f32_e32 v191, 0x42700000, v3
	v_min_f32_e32 v205, 0x42700000, v7
	v_min_f32_e32 v219, 0x42700000, v11
	v_min_f32_e32 v233, 0x42700000, v15
	v_exp_f32_e32 v181, v183
	v_exp_f32_e32 v195, v197
	v_exp_f32_e32 v209, v211
	v_exp_f32_e32 v223, v225
	v_exp_f32_e32 v2, v190
	v_exp_f32_e32 v6, v204
	v_exp_f32_e32 v10, v218
	v_exp_f32_e32 v14, v232
	v_exp_f32_e32 v3, v191
	v_exp_f32_e32 v7, v205
	v_exp_f32_e32 v11, v219
	v_exp_f32_e32 v15, v233
	v_pk_add_f32 v[16:17], v[16:17], 1.0 op_sel_hi:[1,0]
	v_pk_add_f32 v[20:21], v[20:21], 1.0 op_sel_hi:[1,0]
	v_pk_add_f32 v[24:25], v[24:25], 1.0 op_sel_hi:[1,0]
	v_pk_add_f32 v[28:29], v[28:29], 1.0 op_sel_hi:[1,0]
	v_pk_add_f32 v[18:19], v[18:19], 1.0 op_sel_hi:[1,0]
	v_pk_add_f32 v[22:23], v[22:23], 1.0 op_sel_hi:[1,0]
	v_pk_add_f32 v[26:27], v[26:27], 1.0 op_sel_hi:[1,0]
	v_pk_add_f32 v[30:31], v[30:31], 1.0 op_sel_hi:[1,0]
	v_pk_add_f32 v[180:181], v[180:181], 1.0 op_sel_hi:[1,0]
	v_pk_add_f32 v[194:195], v[194:195], 1.0 op_sel_hi:[1,0]
	v_pk_add_f32 v[208:209], v[208:209], 1.0 op_sel_hi:[1,0]
	v_pk_add_f32 v[222:223], v[222:223], 1.0 op_sel_hi:[1,0]
	v_pk_mul_f32 v[182:183], v[16:17], v[18:19]
	v_pk_mul_f32 v[196:197], v[20:21], v[22:23]
	v_pk_mul_f32 v[210:211], v[24:25], v[26:27]
	v_pk_mul_f32 v[224:225], v[28:29], v[30:31]
	v_pk_add_f32 v[2:3], v[2:3], 1.0 op_sel_hi:[1,0]
	v_pk_add_f32 v[6:7], v[6:7], 1.0 op_sel_hi:[1,0]
	v_pk_add_f32 v[10:11], v[10:11], 1.0 op_sel_hi:[1,0]
	v_pk_add_f32 v[14:15], v[14:15], 1.0 op_sel_hi:[1,0]
	v_rcp_f32_e32 v182, v182
	v_rcp_f32_e32 v196, v196
	v_rcp_f32_e32 v210, v210
	v_rcp_f32_e32 v224, v224
	v_rcp_f32_e32 v183, v183
	v_rcp_f32_e32 v197, v197
	v_rcp_f32_e32 v211, v211
	v_rcp_f32_e32 v225, v225
	v_pk_mul_f32 v[184:185], v[2:3], v[180:181]
	v_pk_mul_f32 v[198:199], v[6:7], v[194:195]
	v_pk_mul_f32 v[212:213], v[10:11], v[208:209]
	v_pk_mul_f32 v[226:227], v[14:15], v[222:223]
	v_mov_b64_e32 v[178:179], s[64:65]
	v_mov_b64_e32 v[192:193], s[64:65]
	v_mov_b64_e32 v[206:207], s[64:65]
	v_mov_b64_e32 v[220:221], s[64:65]
	v_rcp_f32_e32 v184, v184
	v_rcp_f32_e32 v198, v198
	v_rcp_f32_e32 v212, v212
	v_rcp_f32_e32 v226, v226
	v_rcp_f32_e32 v185, v185
	v_rcp_f32_e32 v199, v199
	v_rcp_f32_e32 v213, v213
	v_rcp_f32_e32 v227, v227
	v_pk_mul_f32 v[18:19], v[18:19], v[182:183]
	v_pk_mul_f32 v[22:23], v[22:23], v[196:197]
	v_pk_mul_f32 v[26:27], v[26:27], v[210:211]
	v_pk_mul_f32 v[30:31], v[30:31], v[224:225]
	v_pk_mul_f32 v[16:17], v[16:17], v[182:183]
	v_pk_mul_f32 v[20:21], v[20:21], v[196:197]
	v_pk_mul_f32 v[24:25], v[24:25], v[210:211]
	v_pk_mul_f32 v[28:29], v[28:29], v[224:225]
	v_pk_mul_f32 v[182:183], v[106:107], v[18:19]
	v_pk_mul_f32 v[196:197], v[106:107], v[22:23]
	v_pk_mul_f32 v[210:211], v[106:107], v[26:27]
	v_pk_mul_f32 v[224:225], v[106:107], v[30:31]
	v_pk_mul_f32 v[18:19], v[112:113], v[18:19]
	v_pk_mul_f32 v[22:23], v[112:113], v[22:23]
	v_pk_mul_f32 v[26:27], v[112:113], v[26:27]
	v_pk_mul_f32 v[30:31], v[112:113], v[30:31]
	v_exp_f32_e32 v182, v182
	v_exp_f32_e32 v196, v196
	v_exp_f32_e32 v210, v210
	v_exp_f32_e32 v224, v224
	v_pk_fma_f32 v[186:187], v[18:19], s[62:63], v[178:179] op_sel_hi:[1,0,0]
	v_pk_fma_f32 v[200:201], v[22:23], s[62:63], v[192:193] op_sel_hi:[1,0,0]
	v_pk_fma_f32 v[214:215], v[26:27], s[62:63], v[206:207] op_sel_hi:[1,0,0]
	v_pk_fma_f32 v[228:229], v[30:31], s[62:63], v[220:221] op_sel_hi:[1,0,0]
	v_exp_f32_e32 v183, v183
	v_exp_f32_e32 v197, v197
	v_exp_f32_e32 v211, v211
	v_exp_f32_e32 v225, v225
	v_pk_mul_f32 v[180:181], v[180:181], v[184:185]
	v_pk_mul_f32 v[194:195], v[194:195], v[198:199]
	v_pk_mul_f32 v[208:209], v[208:209], v[212:213]
	v_pk_mul_f32 v[222:223], v[222:223], v[226:227]
	v_pk_mul_f32 v[2:3], v[2:3], v[184:185]
	v_pk_mul_f32 v[6:7], v[6:7], v[198:199]
	v_pk_mul_f32 v[10:11], v[10:11], v[212:213]
	v_pk_mul_f32 v[14:15], v[14:15], v[226:227]
	v_pk_fma_f32 v[184:185], v[18:19], v[186:187], s[66:67] op_sel_hi:[1,1,0]
	v_pk_fma_f32 v[198:199], v[22:23], v[200:201], s[66:67] op_sel_hi:[1,1,0]
	v_pk_fma_f32 v[212:213], v[26:27], v[214:215], s[66:67] op_sel_hi:[1,1,0]
	v_pk_fma_f32 v[226:227], v[30:31], v[228:229], s[66:67] op_sel_hi:[1,1,0]
	v_pk_mul_f32 v[186:187], v[106:107], v[180:181]
	v_pk_mul_f32 v[200:201], v[106:107], v[194:195]
	v_pk_mul_f32 v[214:215], v[106:107], v[208:209]
	v_pk_mul_f32 v[228:229], v[106:107], v[222:223]
	v_pk_fma_f32 v[184:185], v[18:19], v[184:185], s[68:69] op_sel_hi:[1,1,0]
	v_pk_fma_f32 v[198:199], v[22:23], v[198:199], s[68:69] op_sel_hi:[1,1,0]
	v_pk_fma_f32 v[212:213], v[26:27], v[212:213], s[68:69] op_sel_hi:[1,1,0]
	v_pk_fma_f32 v[226:227], v[30:31], v[226:227], s[68:69] op_sel_hi:[1,1,0]
	v_pk_mul_f32 v[180:181], v[112:113], v[180:181]
	v_pk_mul_f32 v[194:195], v[112:113], v[194:195]
	v_pk_mul_f32 v[208:209], v[112:113], v[208:209]
	v_pk_mul_f32 v[222:223], v[112:113], v[222:223]
	v_pk_fma_f32 v[184:185], v[18:19], v[184:185], 0.5 op_sel_hi:[1,1,0]
	v_pk_fma_f32 v[198:199], v[22:23], v[198:199], 0.5 op_sel_hi:[1,1,0]
	v_pk_fma_f32 v[212:213], v[26:27], v[212:213], 0.5 op_sel_hi:[1,1,0]
	v_pk_fma_f32 v[226:227], v[30:31], v[226:227], 0.5 op_sel_hi:[1,1,0]
	v_pk_fma_f32 v[178:179], v[180:181], s[62:63], v[178:179] op_sel_hi:[1,0,0]
	v_pk_fma_f32 v[192:193], v[194:195], s[62:63], v[192:193] op_sel_hi:[1,0,0]
	v_pk_fma_f32 v[206:207], v[208:209], s[62:63], v[206:207] op_sel_hi:[1,0,0]
	v_pk_fma_f32 v[220:221], v[222:223], s[62:63], v[220:221] op_sel_hi:[1,0,0]
	v_pk_fma_f32 v[184:185], v[18:19], v[184:185], 1.0 op_sel_hi:[1,1,0]
	v_pk_fma_f32 v[198:199], v[22:23], v[198:199], 1.0 op_sel_hi:[1,1,0]
	v_pk_fma_f32 v[212:213], v[26:27], v[212:213], 1.0 op_sel_hi:[1,1,0]
	v_pk_fma_f32 v[226:227], v[30:31], v[226:227], 1.0 op_sel_hi:[1,1,0]
	v_exp_f32_e32 v186, v186
	v_exp_f32_e32 v200, v200
	v_exp_f32_e32 v214, v214
	v_exp_f32_e32 v228, v228
	v_exp_f32_e32 v187, v187
	v_exp_f32_e32 v201, v201
	v_exp_f32_e32 v215, v215
	v_exp_f32_e32 v229, v229
	v_pk_fma_f32 v[178:179], v[180:181], v[178:179], s[66:67] op_sel_hi:[1,1,0]
	v_pk_fma_f32 v[192:193], v[194:195], v[192:193], s[66:67] op_sel_hi:[1,1,0]
	v_pk_fma_f32 v[206:207], v[208:209], v[206:207], s[66:67] op_sel_hi:[1,1,0]
	v_pk_fma_f32 v[220:221], v[222:223], v[220:221], s[66:67] op_sel_hi:[1,1,0]
	v_pk_fma_f32 v[188:189], v[182:183], v[182:183], 1.0 op_sel_hi:[1,1,0] neg_lo:[1,0,0] neg_hi:[1,0,0]
	v_pk_fma_f32 v[202:203], v[196:197], v[196:197], 1.0 op_sel_hi:[1,1,0] neg_lo:[1,0,0] neg_hi:[1,0,0]
	v_pk_fma_f32 v[216:217], v[210:211], v[210:211], 1.0 op_sel_hi:[1,1,0] neg_lo:[1,0,0] neg_hi:[1,0,0]
	v_pk_fma_f32 v[230:231], v[224:225], v[224:225], 1.0 op_sel_hi:[1,1,0] neg_lo:[1,0,0] neg_hi:[1,0,0]
	v_pk_mul_f32 v[184:185], v[18:19], v[184:185] neg_lo:[0,1] neg_hi:[0,1]
	v_pk_mul_f32 v[198:199], v[22:23], v[198:199] neg_lo:[0,1] neg_hi:[0,1]
	v_pk_mul_f32 v[212:213], v[26:27], v[212:213] neg_lo:[0,1] neg_hi:[0,1]
	v_pk_mul_f32 v[226:227], v[30:31], v[226:227] neg_lo:[0,1] neg_hi:[0,1]
	v_cmp_lt_f32_e64 s[16:17], s10, v19
	v_cmp_lt_f32_e64 s[18:19], s10, v18
	v_pk_fma_f32 v[178:179], v[180:181], v[178:179], s[68:69] op_sel_hi:[1,1,0]
	v_cndmask_b32_e64 v185, v189, v185, s[16:17]
	v_cndmask_b32_e64 v184, v188, v184, s[18:19]
	v_cmp_lt_f32_e64 s[16:17], s10, v23
	v_cmp_lt_f32_e64 s[18:19], s10, v22
	v_pk_fma_f32 v[192:193], v[194:195], v[192:193], s[68:69] op_sel_hi:[1,1,0]
	v_cndmask_b32_e64 v199, v203, v199, s[16:17]
	v_cndmask_b32_e64 v198, v202, v198, s[18:19]
	v_cmp_lt_f32_e64 s[16:17], s10, v27
	v_cmp_lt_f32_e64 s[18:19], s10, v26
	v_pk_fma_f32 v[206:207], v[208:209], v[206:207], s[68:69] op_sel_hi:[1,1,0]
	v_cndmask_b32_e64 v213, v217, v213, s[16:17]
	v_cndmask_b32_e64 v212, v216, v212, s[18:19]
	v_cmp_lt_f32_e64 s[16:17], s10, v31
	v_cmp_lt_f32_e64 s[18:19], s10, v30
	v_pk_fma_f32 v[220:221], v[222:223], v[220:221], s[68:69] op_sel_hi:[1,1,0]
	v_cndmask_b32_e64 v227, v231, v227, s[16:17]
	v_cndmask_b32_e64 v226, v230, v226, s[18:19]
	v_pk_fma_f32 v[178:179], v[180:181], v[178:179], 0.5 op_sel_hi:[1,1,0]
	v_pk_fma_f32 v[192:193], v[194:195], v[192:193], 0.5 op_sel_hi:[1,1,0]
	v_pk_fma_f32 v[206:207], v[208:209], v[206:207], 0.5 op_sel_hi:[1,1,0]
	v_pk_fma_f32 v[220:221], v[222:223], v[220:221], 0.5 op_sel_hi:[1,1,0]
	v_sqrt_f32_e32 v184, v184
	v_sqrt_f32_e32 v198, v198
	v_sqrt_f32_e32 v212, v212
	v_sqrt_f32_e32 v226, v226
	v_sqrt_f32_e32 v185, v185
	v_sqrt_f32_e32 v199, v199
	v_sqrt_f32_e32 v213, v213
	v_sqrt_f32_e32 v227, v227
	v_pk_fma_f32 v[178:179], v[180:181], v[178:179], 1.0 op_sel_hi:[1,1,0]
	v_pk_fma_f32 v[192:193], v[194:195], v[192:193], 1.0 op_sel_hi:[1,1,0]
	v_pk_fma_f32 v[206:207], v[208:209], v[206:207], 1.0 op_sel_hi:[1,1,0]
	v_pk_fma_f32 v[220:221], v[222:223], v[220:221], 1.0 op_sel_hi:[1,1,0]
	v_pk_fma_f32 v[18:19], v[186:187], v[186:187], 1.0 op_sel_hi:[1,1,0] neg_lo:[1,0,0] neg_hi:[1,0,0]
	v_pk_fma_f32 v[22:23], v[200:201], v[200:201], 1.0 op_sel_hi:[1,1,0] neg_lo:[1,0,0] neg_hi:[1,0,0]
	v_pk_fma_f32 v[26:27], v[214:215], v[214:215], 1.0 op_sel_hi:[1,1,0] neg_lo:[1,0,0] neg_hi:[1,0,0]
	v_pk_fma_f32 v[30:31], v[228:229], v[228:229], 1.0 op_sel_hi:[1,1,0] neg_lo:[1,0,0] neg_hi:[1,0,0]
	v_pk_mul_f32 v[178:179], v[180:181], v[178:179] neg_lo:[0,1] neg_hi:[0,1]
	v_pk_mul_f32 v[192:193], v[194:195], v[192:193] neg_lo:[0,1] neg_hi:[0,1]
	v_pk_mul_f32 v[206:207], v[208:209], v[206:207] neg_lo:[0,1] neg_hi:[0,1]
	v_pk_mul_f32 v[220:221], v[222:223], v[220:221] neg_lo:[0,1] neg_hi:[0,1]
	v_cmp_lt_f32_e64 s[16:17], s10, v181
	v_cmp_lt_f32_e64 s[18:19], s10, v180
	v_pk_mul_f32 v[16:17], v[16:17], v[184:185]
	v_cndmask_b32_e64 v179, v19, v179, s[16:17]
	v_cndmask_b32_e64 v178, v18, v178, s[18:19]
	v_cmp_lt_f32_e64 s[16:17], s10, v195
	v_cmp_lt_f32_e64 s[18:19], s10, v194
	v_pk_mul_f32 v[20:21], v[20:21], v[198:199]
	v_cndmask_b32_e64 v193, v23, v193, s[16:17]
	v_cndmask_b32_e64 v192, v22, v192, s[18:19]
	v_cmp_lt_f32_e64 s[16:17], s10, v209
	v_cmp_lt_f32_e64 s[18:19], s10, v208
	v_pk_mul_f32 v[24:25], v[24:25], v[212:213]
	v_cndmask_b32_e64 v207, v27, v207, s[16:17]
	v_cndmask_b32_e64 v206, v26, v206, s[18:19]
	v_cmp_lt_f32_e64 s[16:17], s10, v223
	v_cmp_lt_f32_e64 s[18:19], s10, v222
	v_pk_mul_f32 v[28:29], v[28:29], v[226:227]
	v_cndmask_b32_e64 v221, v31, v221, s[16:17]
	v_cndmask_b32_e64 v220, v30, v220, s[18:19]
	v_sqrt_f32_e32 v178, v178
	v_sqrt_f32_e32 v192, v192
	v_sqrt_f32_e32 v206, v206
	v_sqrt_f32_e32 v220, v220
	v_sqrt_f32_e32 v179, v179
	v_sqrt_f32_e32 v193, v193
	v_sqrt_f32_e32 v207, v207
	v_sqrt_f32_e32 v221, v221
	v_pk_mul_f32 v[16:17], v[152:153], v[16:17]
	v_pk_mul_f32 v[20:21], v[156:157], v[20:21]
	v_pk_mul_f32 v[24:25], v[160:161], v[24:25]
	v_pk_mul_f32 v[28:29], v[164:165], v[28:29]
	v_pk_mul_f32 v[178:179], v[2:3], v[178:179]
	v_pk_mul_f32 v[192:193], v[6:7], v[192:193]
	v_pk_mul_f32 v[206:207], v[10:11], v[206:207]
	v_pk_mul_f32 v[220:221], v[14:15], v[220:221]
	v_pk_mul_f32 v[178:179], v[154:155], v[178:179]
	v_pk_mul_f32 v[192:193], v[158:159], v[192:193]
	v_pk_mul_f32 v[206:207], v[162:163], v[206:207]
	v_pk_mul_f32 v[220:221], v[166:167], v[220:221]
	v_mul_f32_e32 v0, v182, v183
	v_fma_f32 v4, v183, v16, v17
	v_mul_f32_e32 v1, v196, v197
	v_fma_f32 v5, v197, v20, v21
	v_mul_f32_e32 v2, v210, v211
	v_fma_f32 v6, v211, v24, v25
	v_mul_f32_e32 v3, v224, v225
	v_fma_f32 v7, v225, v28, v29
	v_mul_f32_e32 v0, v0, v186
	v_fma_f32 v4, v186, v4, v178
	v_mul_f32_e32 v1, v1, v200
	v_fma_f32 v5, v200, v5, v192
	v_mul_f32_e32 v2, v2, v214
	v_fma_f32 v6, v214, v6, v206
	v_mul_f32_e32 v3, v3, v228
	v_fma_f32 v7, v228, v7, v220
	v_mul_f32_e32 v0, v0, v187
	v_fma_f32 v4, v187, v4, v179
	v_mul_f32_e32 v1, v1, v201
	v_fma_f32 v5, v201, v5, v193
	v_mul_f32_e32 v2, v2, v215
	v_fma_f32 v6, v215, v6, v207
	v_mul_f32_e32 v3, v3, v229
	v_fma_f32 v7, v229, v7, v221
	v_mov_b32_e32 v8, v0
	v_mov_b32_e32 v9, v1
	v_mov_b32_e32 v10, v2
	v_mov_b32_e32 v11, v3
	v_mov_b32_e32 v12, v4
	v_mov_b32_e32 v13, v5
	v_mov_b32_e32 v14, v6
	v_mov_b32_e32 v15, v7
	s_nop 1
	v_permlane32_swap_b32_e32 v0, v8
	v_permlane32_swap_b32_e32 v1, v9
	v_permlane32_swap_b32_e32 v2, v10
	v_permlane32_swap_b32_e32 v3, v11
	v_permlane32_swap_b32_e32 v4, v12
	v_permlane32_swap_b32_e32 v5, v13
	v_permlane32_swap_b32_e32 v6, v14
	v_permlane32_swap_b32_e32 v7, v15
	s_nop 0
	v_mov_b32_e32 v152, v0
	v_mov_b32_e32 v160, v4
	v_mul_f32_e32 v153, v8, v152
	v_fma_f32 v161, v8, v160, v12
	v_mul_f32_e32 v154, v1, v153
	v_fma_f32 v162, v1, v161, v5
	v_mul_f32_e32 v155, v9, v154
	v_fma_f32 v163, v9, v162, v13
	v_mul_f32_e32 v156, v2, v155
	v_fma_f32 v164, v2, v163, v6
	v_mul_f32_e32 v157, v10, v156
	v_fma_f32 v165, v10, v164, v14
	v_mul_f32_e32 v158, v3, v157
	v_fma_f32 v166, v3, v165, v7
	v_mul_f32_e32 v159, v11, v158
	v_fma_f32 v167, v11, v166, v15
	s_lshl_b32 s16, s24, 12
	s_and_b32 s16, s16, 0x1000
	s_add_i32 s16, s16, 0x20000
	s_lshr_b32 s17, s90, 5
	s_add_i32 s17, s17, s16
	v_lshl_add_u32 v251, v133, 2, s17
	v_lshl_add_u32 v177, v133, 2, s16
	ds_write2_b32 v251, v159, v167 offset1:32
	s_mov_b32 vcc_lo, 0
	s_mov_b32 vcc_hi, -1
	v_mov_b32_e32 v253, 1.0
	v_cndmask_b32_e32 v8, v253, v152, vcc
	v_cndmask_b32_e32 v12, 0, v160, vcc
	v_cndmask_b32_e32 v9, v153, v154, vcc
	v_cndmask_b32_e32 v13, v161, v162, vcc
	v_cndmask_b32_e32 v10, v155, v156, vcc
	v_cndmask_b32_e32 v14, v163, v164, vcc
	v_cndmask_b32_e32 v11, v157, v158, vcc
	v_cndmask_b32_e32 v15, v165, v166, vcc
	v_add_u32_e32 v253, 0x400, v177
	s_waitcnt lgkmcnt(0)
	s_barrier
	ds_read2_b32 v[152:153], v177 offset0:0 offset1:32
	ds_read2_b32 v[154:155], v177 offset0:64 offset1:96
	ds_read2_b32 v[156:157], v177 offset0:128 offset1:160
	ds_read2_b32 v[158:159], v177 offset0:192 offset1:224
	ds_read2_b32 v[160:161], v253 offset0:0 offset1:32
	ds_read2_b32 v[162:163], v253 offset0:64 offset1:96
	ds_read2_b32 v[164:165], v253 offset0:128 offset1:160
	ds_read2_b32 v[166:167], v253 offset0:192 offset1:224
	s_lshr_b32 s17, s90, 13
	v_mov_b32_e32 v251, v105
	s_cmp_eq_u32 s17, 0
	s_cselect_b64 s[18:19], -1, 0
	s_waitcnt lgkmcnt(7)
	v_cndmask_b32_e64 v251, v251, v105, s[18:19]
	v_fma_f32 v105, v152, v105, v153
	s_cmp_eq_u32 s17, 1
	s_cselect_b64 s[18:19], -1, 0
	s_waitcnt lgkmcnt(6)
	v_cndmask_b32_e64 v251, v251, v105, s[18:19]
	v_fma_f32 v105, v154, v105, v155
	s_cmp_eq_u32 s17, 2
	s_cselect_b64 s[18:19], -1, 0
	s_waitcnt lgkmcnt(5)
	v_cndmask_b32_e64 v251, v251, v105, s[18:19]
	v_fma_f32 v105, v156, v105, v157
	s_cmp_eq_u32 s17, 3
	s_cselect_b64 s[18:19], -1, 0
	s_waitcnt lgkmcnt(4)
	v_cndmask_b32_e64 v251, v251, v105, s[18:19]
	v_fma_f32 v105, v158, v105, v159
	s_cmp_eq_u32 s17, 4
	s_cselect_b64 s[18:19], -1, 0
	s_waitcnt lgkmcnt(3)
	v_cndmask_b32_e64 v251, v251, v105, s[18:19]
	v_fma_f32 v105, v160, v105, v161
	s_cmp_eq_u32 s17, 5
	s_cselect_b64 s[18:19], -1, 0
	s_waitcnt lgkmcnt(2)
	v_cndmask_b32_e64 v251, v251, v105, s[18:19]
	v_fma_f32 v105, v162, v105, v163
	s_cmp_eq_u32 s17, 6
	s_cselect_b64 s[18:19], -1, 0
	s_waitcnt lgkmcnt(1)
	v_cndmask_b32_e64 v251, v251, v105, s[18:19]
	v_fma_f32 v105, v164, v105, v165
	s_cmp_eq_u32 s17, 7
	s_cselect_b64 s[18:19], -1, 0
	s_waitcnt lgkmcnt(0)
	v_cndmask_b32_e64 v251, v251, v105, s[18:19]
	v_fma_f32 v105, v166, v105, v167
	v_fma_f32 v0, v8, v251, v12
	v_fma_f32 v1, v9, v251, v13
	v_fma_f32 v2, v10, v251, v14
	v_fma_f32 v3, v11, v251, v15
	v_fma_f32 v16, v182, v0, v16
	v_fma_f32 v20, v196, v1, v20
	v_fma_f32 v24, v210, v2, v24
	v_fma_f32 v28, v224, v3, v28
	v_fma_f32 v17, v183, v16, v17
	v_fma_f32 v21, v197, v20, v21
	v_fma_f32 v25, v211, v24, v25
	v_fma_f32 v29, v225, v28, v29
	v_fma_f32 v178, v186, v17, v178
	v_fma_f32 v192, v200, v21, v192
	v_fma_f32 v206, v214, v25, v206
	v_fma_f32 v220, v228, v29, v220
	v_fma_f32 v179, v187, v178, v179
	v_fma_f32 v193, v201, v192, v193
	v_fma_f32 v207, v215, v206, v207
	v_fma_f32 v221, v229, v220, v221
	ds_write_b32 v250, v16
	ds_write_b32 v250, v17 offset:128
	ds_write_b32 v250, v178 offset:256
	ds_write_b32 v250, v179 offset:384
	ds_write_b32 v250, v20 offset:1024
	ds_write_b32 v250, v21 offset:1152
	ds_write_b32 v250, v192 offset:1280
	ds_write_b32 v250, v193 offset:1408
	ds_write_b32 v250, v24 offset:2048
	ds_write_b32 v250, v25 offset:2176
	ds_write_b32 v250, v206 offset:2304
	ds_write_b32 v250, v207 offset:2432
	ds_write_b32 v250, v28 offset:3072
	ds_write_b32 v250, v29 offset:3200
	ds_write_b32 v250, v220 offset:3328
	ds_write_b32 v250, v221 offset:3456
	s_waitcnt lgkmcnt(0)
	v_lshlrev_b32_e32 v12, 7, v114
	v_lshlrev_b32_e32 v14, 6, v132
	s_waitcnt lgkmcnt(0)
	v_add3_u32 v12, s33, v12, v14
	ds_read_b128 v[14:17], v12
	ds_read_b128 v[18:21], v12 offset:16
	ds_read_b128 v[22:25], v12 offset:32
	ds_read_b128 v[26:29], v12 offset:48
	s_waitcnt lgkmcnt(3)
	v_mul_f32_e32 v12, v15, v15
	v_mul_f32_e32 v30, v17, v17
	v_fmac_f32_e32 v12, v14, v14
	v_fmac_f32_e32 v30, v16, v16
	v_add_f32_e32 v12, v12, v30
	s_waitcnt lgkmcnt(2)
	v_mul_f32_e32 v30, v19, v19
	v_fmac_f32_e32 v30, v18, v18
	v_add_f32_e32 v12, v12, v30
	v_mul_f32_e32 v30, v21, v21
	v_fmac_f32_e32 v30, v20, v20
	v_add_f32_e32 v12, v30, v12
	s_waitcnt lgkmcnt(1)
	v_mul_f32_e32 v30, v23, v23
	v_fmac_f32_e32 v30, v22, v22
	v_add_f32_e32 v12, v30, v12
	v_mul_f32_e32 v30, v25, v25
	v_fmac_f32_e32 v30, v24, v24
	v_add_f32_e32 v12, v30, v12
	s_waitcnt lgkmcnt(0)
	v_mul_f32_e32 v30, v27, v27
	v_fmac_f32_e32 v30, v26, v26
	v_add_f32_e32 v12, v30, v12
	v_mul_f32_e32 v30, v29, v29
	v_fmac_f32_e32 v30, v28, v28
	v_add_f32_e32 v12, v30, v12
	s_waitcnt vmcnt(0)
	v_lshlrev_b32_e32 v30, 16, v244
	v_and_b32_e32 v244, 0xffff0000, v244
	v_mul_f32_e32 v14, v14, v30
	v_mul_f32_e32 v244, v15, v244
	v_cvt_pk_bf16_f32 v244, v14, v244
	v_lshlrev_b32_e32 v14, 16, v245
	v_and_b32_e32 v245, 0xffff0000, v245
	v_mul_f32_e32 v14, v16, v14
	v_mul_f32_e32 v245, v17, v245
	v_cvt_pk_bf16_f32 v245, v14, v245
	v_lshlrev_b32_e32 v14, 16, v246
	v_and_b32_e32 v246, 0xffff0000, v246
	v_mul_f32_e32 v14, v18, v14
	v_mul_f32_e32 v246, v19, v246
	v_cvt_pk_bf16_f32 v246, v14, v246
	v_lshlrev_b32_e32 v14, 16, v247
	v_and_b32_e32 v247, 0xffff0000, v247
	v_mul_f32_e32 v14, v20, v14
	v_mul_f32_e32 v247, v21, v247
	v_cvt_pk_bf16_f32 v247, v14, v247
	v_lshlrev_b32_e32 v14, 16, v240
	v_and_b32_e32 v240, 0xffff0000, v240
	v_mul_f32_e32 v14, v22, v14
	v_mul_f32_e32 v240, v23, v240
	v_cvt_pk_bf16_f32 v14, v14, v240
	v_lshlrev_b32_e32 v240, 16, v241
	v_mul_f32_e32 v240, v24, v240
	v_and_b32_e32 v241, 0xffff0000, v241
	v_mul_f32_e32 v241, v25, v241
	v_cvt_pk_bf16_f32 v15, v240, v241
	v_lshlrev_b32_e32 v240, 16, v242
	v_mul_f32_e32 v240, v26, v240
	v_and_b32_e32 v241, 0xffff0000, v242
	v_mul_f32_e32 v241, v27, v241
	v_cvt_pk_bf16_f32 v16, v240, v241
	v_lshlrev_b32_e32 v240, 16, v243
	v_mul_f32_e32 v241, v28, v240
	v_and_b32_e32 v240, 0xffff0000, v243
	v_and_b32_e32 v243, 64, v126
	v_mul_f32_e32 v242, v29, v240
	v_xor_b32_e32 v240, 1, v126
	v_add_u32_e32 v243, 64, v243
	v_cmp_lt_i32_e64 s[16:17], v240, v243
	v_cvt_pk_bf16_f32 v17, v241, v242
	global_store_dwordx4 v[248:249], v[244:247], off
	global_store_dwordx4 v[248:249], v[14:17], off offset:16
	v_cndmask_b32_e64 v240, v126, v240, s[16:17]
	v_lshlrev_b32_e32 v240, 2, v240
	ds_bpermute_b32 v240, v240, v12
	v_cmp_eq_u32_e64 s[16:17], 0, v132
	s_and_saveexec_b64 s[18:19], s[16:17]
	s_cbranch_execz .LBB0_360
	s_lshl_b64 s[0:1], s[52:53], 2
	s_add_u32 s0, s25, s0
	s_addc_u32 s1, s26, s1
	v_ashrrev_i32_e32 v115, 31, v114
	v_lshl_add_u64 v[242:243], v[114:115], 2, s[0:1]
	s_waitcnt lgkmcnt(0)
	v_add_f32_e32 v240, v12, v240
	global_store_dword v[242:243], v240, off
	s_branch .LBB0_360
